# first waits of the post and RMSNorm loops changed from vmcnt(0) to the counted value (11 / 7) so compute starts when the oldest load lands
# speedup vs baseline: 1.0041x; 1.0041x over previous
; DI int bidx() { int t = blockIdx.x; asm volatile("" : "+s"(t)); return t; }
; DI void phase_post(PP p, int l) {
;     ...
;     for (int base = (bidx() * 8 + wid) * 8; base < MT * 8; base += nw * 8) {
;         f32x2 y[4]; unsigned bv[4], g[4];
; #pragma unroll
;         for (int i = 0; i < 4; ++i) {
;             const int it = base + 2 * i + ip; const size_t gr = (size_t)(it >> 3); const int hd = (it & 7) * 64 + 2 * cp;
;             y[i] = __builtin_nontemporal_load((const f32x2*)(y32 + gr * 512 + hd)); bv[i] = __builtin_nontemporal_load((const unsigned*)(ob + gr * 512 + hd)); g[i] = __builtin_nontemporal_load((const unsigned*)(lro + gr * LR_LD + 1024 + hd));
;         }
; #pragma unroll
;         for (int i = 0; i < 4; ++i) {
;             const int it = base + 2 * i + ip; const size_t gr = (size_t)(it >> 3); const int hd = (it & 7) * 64 + 2 * cp;
;             const float mean = half_sum(y[i][0] + y[i][1]) * (1.f / 64.f); const f32x2 d = y[i] - mean; const float var = half_sum(d[0] * d[0] + d[1] * d[1]) * (1.f / 64.f);
.LBB0_45:
	v_ashrrev_i32_e32 v32, 3, v30
	s_mov_b64 s[16:17], 0xc600800
	v_ashrrev_i32_e32 v33, 31, v32
	v_mad_i64_i32 v[34:35], s[22:23], v32, s63, v[22:23]
	v_lshl_add_u64 v[34:35], v[34:35], 0, s[16:17]
	v_lshlrev_b64 v[36:37], 11, v[32:33]
	v_lshlrev_b64 v[32:33], 10, v[32:33]
	v_lshl_add_u64 v[36:37], v[18:19], 0, v[36:37]
	v_lshl_add_u64 v[38:39], v[34:35], 0, v[0:1]
	v_lshl_add_u64 v[40:41], v[34:35], 0, v[24:25]
	v_lshl_add_u64 v[42:43], v[34:35], 0, v[26:27]
	v_lshl_add_u64 v[34:35], v[34:35], 0, v[28:29]
	v_lshl_add_u64 v[32:33], v[20:21], 0, v[32:33]
	global_load_dwordx2 v[44:45], v[36:37], off nt
	global_load_dword v31, v[32:33], off nt
	global_load_dword v46, v[38:39], off nt
	s_nop 0
	global_load_dwordx2 v[38:39], v[36:37], off offset:512 nt
	global_load_dword v47, v[32:33], off offset:256 nt
	global_load_dword v48, v[40:41], off nt
	s_nop 0
	global_load_dwordx2 v[40:41], v[36:37], off offset:1024 nt
	global_load_dword v49, v[32:33], off offset:512 nt
	s_nop 0
	global_load_dword v42, v[42:43], off nt
	s_nop 0
	global_load_dwordx2 v[36:37], v[36:37], off offset:1536 nt
	s_nop 0
	global_load_dword v34, v[34:35], off nt
	s_nop 0
	global_load_dword v35, v[32:33], off offset:768 nt
	v_add_u32_e32 v30, v253, v30
	s_mov_b32 s18, 0x41fff
	v_cmp_lt_i32_e32 vcc, s18, v30
	s_or_b64 s[10:11], vcc, s[10:11]
	s_waitcnt vmcnt(11)
	v_add_f32_e32 v43, v44, v45
	s_waitcnt vmcnt(10)
	v_lshlrev_b32_e32 v50, 16, v31
	s_waitcnt vmcnt(9)
	v_lshlrev_b32_e32 v51, 16, v46
	v_and_b32_e32 v52, 0xffff0000, v46
	s_waitcnt vmcnt(8)
	v_add_f32_e32 v46, v38, v39
	s_waitcnt vmcnt(7)
	v_lshlrev_b32_e32 v53, 16, v47
	v_and_b32_e32 v54, 0xffff0000, v47
	s_waitcnt vmcnt(5)
	v_add_f32_e32 v47, v40, v41
	s_waitcnt vmcnt(3)
	v_lshlrev_b32_e32 v59, 16, v42
	v_and_b32_e32 v60, 0xffff0000, v42
	s_waitcnt vmcnt(1)
	v_lshlrev_b32_e32 v63, 16, v34
	v_and_b32_e32 v64, 0xffff0000, v34
	v_add_f32_dpp v34, v43, v43 quad_perm:[1,0,3,2] row_mask:0xf bank_mask:0xf bound_ctrl:1
	v_add_f32_e32 v42, v36, v37
	s_waitcnt vmcnt(0)
; DI unsigned cvtpk(float lo, float hi) { unsigned r; asm volatile("v_cvt_pk_bf16_f32 %0, %1, %2" : "=v"(r) : "v"(lo), "v"(hi)); return r; }
; DI float lo_bf(unsigned u) { return __uint_as_float(u << 16); }
; DI float hi_bf(unsigned u) { return __uint_as_float(u & 0xFFFF0000u); }
; DI void phase_post(PP p, int l) {
;     ...
; #pragma unroll
;         for (int i = 0; i < 4; ++i) {
;             const int it = base + 2 * i + ip; const size_t gr = (size_t)(it >> 3); const int hd = (it & 7) * 64 + 2 * cp;
;             const float mean = half_sum(y[i][0] + y[i][1]) * (1.f / 64.f); const f32x2 d = y[i] - mean; const float var = half_sum(d[0] * d[0] + d[1] * d[1]) * (1.f / 64.f);
;             const float rs = __builtin_amdgcn_rsqf(var + 64e-5f);
;             const float y0 = d[0] * rs * gg[i][0] + gb[i][0] + lo_bf(bv[i]), y1 = d[1] * rs * gg[i][1] + gb[i][1] + hi_bf(bv[i]);
;             const unsigned r16 = cvtpk(y0, y1);
;             *(unsigned*)(ob + gr * 512 + hd) = cvtpk(lo_bf(r16) * lo_bf(g[i]), hi_bf(r16) * hi_bf(g[i]));
;         }
;     }
	v_lshlrev_b32_e32 v61, 16, v35
	v_and_b32_e32 v62, 0xffff0000, v35
	v_add_f32_dpp v35, v46, v46 quad_perm:[1,0,3,2] row_mask:0xf bank_mask:0xf bound_ctrl:1
	v_add_f32_dpp v34, v34, v34 quad_perm:[2,3,0,1] row_mask:0xf bank_mask:0xf bound_ctrl:1
	v_add_f32_dpp v43, v47, v47 quad_perm:[1,0,3,2] row_mask:0xf bank_mask:0xf bound_ctrl:1
	v_add_f32_dpp v42, v42, v42 quad_perm:[1,0,3,2] row_mask:0xf bank_mask:0xf bound_ctrl:1
	v_add_f32_dpp v35, v35, v35 quad_perm:[2,3,0,1] row_mask:0xf bank_mask:0xf bound_ctrl:1
	v_add_f32_dpp v34, v34, v34 row_half_mirror row_mask:0xf bank_mask:0xf bound_ctrl:1
	v_add_f32_dpp v43, v43, v43 quad_perm:[2,3,0,1] row_mask:0xf bank_mask:0xf bound_ctrl:1
	v_add_f32_dpp v42, v42, v42 quad_perm:[2,3,0,1] row_mask:0xf bank_mask:0xf bound_ctrl:1
	v_add_f32_dpp v35, v35, v35 row_half_mirror row_mask:0xf bank_mask:0xf bound_ctrl:1
	v_add_f32_dpp v34, v34, v34 row_mirror row_mask:0xf bank_mask:0xf bound_ctrl:1
	v_add_f32_dpp v43, v43, v43 row_half_mirror row_mask:0xf bank_mask:0xf bound_ctrl:1
	v_add_f32_dpp v42, v42, v42 row_half_mirror row_mask:0xf bank_mask:0xf bound_ctrl:1
	v_add_f32_dpp v35, v35, v35 row_mirror row_mask:0xf bank_mask:0xf bound_ctrl:1
	v_mov_b32_e32 v46, v34
	v_add_f32_dpp v43, v43, v43 row_mirror row_mask:0xf bank_mask:0xf bound_ctrl:1
	v_add_f32_dpp v42, v42, v42 row_mirror row_mask:0xf bank_mask:0xf bound_ctrl:1
	v_mov_b32_e32 v47, v35
	v_permlane16_swap_b32_e32 v34, v46
	v_lshlrev_b32_e32 v55, 16, v48
	v_and_b32_e32 v56, 0xffff0000, v48
	v_lshlrev_b32_e32 v57, 16, v49
	v_and_b32_e32 v58, 0xffff0000, v49
	v_mov_b32_e32 v48, v43
	v_mov_b32_e32 v49, v42
	v_permlane16_swap_b32_e32 v35, v47
	v_add_f32_e32 v34, v34, v46
	v_permlane16_swap_b32_e32 v43, v48
	v_permlane16_swap_b32_e32 v42, v49
	v_add_f32_e32 v35, v35, v47
	v_mul_f32_e32 v34, 0x3c800000, v34
	v_add_f32_e32 v43, v43, v48
	v_add_f32_e32 v47, v42, v49
	v_mul_f32_e32 v42, 0x3c800000, v35
	v_pk_add_f32 v[34:35], v[44:45], v[34:35] op_sel_hi:[1,0] neg_lo:[0,1] neg_hi:[0,1]
	v_mul_f32_e32 v46, 0x3c800000, v43
	v_pk_add_f32 v[38:39], v[38:39], v[42:43] op_sel_hi:[1,0] neg_lo:[0,1] neg_hi:[0,1]
	v_pk_mul_f32 v[42:43], v[34:35], v[34:35]
	v_pk_add_f32 v[40:41], v[40:41], v[46:47] op_sel_hi:[1,0] neg_lo:[0,1] neg_hi:[0,1]
	v_add_f32_e32 v42, v42, v43
	v_mul_f32_e32 v48, 0x3c800000, v47
	v_pk_mul_f32 v[44:45], v[38:39], v[38:39]
	v_add_f32_dpp v42, v42, v42 quad_perm:[1,0,3,2] row_mask:0xf bank_mask:0xf bound_ctrl:1
	v_pk_mul_f32 v[46:47], v[40:41], v[40:41]
	v_add_f32_e32 v43, v44, v45
	v_add_f32_dpp v42, v42, v42 quad_perm:[2,3,0,1] row_mask:0xf bank_mask:0xf bound_ctrl:1
	v_add_f32_e32 v44, v46, v47
	v_add_f32_dpp v43, v43, v43 quad_perm:[1,0,3,2] row_mask:0xf bank_mask:0xf bound_ctrl:1
	v_add_f32_dpp v42, v42, v42 row_half_mirror row_mask:0xf bank_mask:0xf bound_ctrl:1
	v_add_f32_dpp v44, v44, v44 quad_perm:[1,0,3,2] row_mask:0xf bank_mask:0xf bound_ctrl:1
	v_add_f32_dpp v43, v43, v43 quad_perm:[2,3,0,1] row_mask:0xf bank_mask:0xf bound_ctrl:1
	v_add_f32_dpp v42, v42, v42 row_mirror row_mask:0xf bank_mask:0xf bound_ctrl:1
	v_mov_b32_e32 v46, v42
	s_nop 1
	v_permlane16_swap_b32_e32 v42, v46
	v_add_f32_e32 v42, v42, v46
	v_add_f32_dpp v43, v43, v43 row_half_mirror row_mask:0xf bank_mask:0xf bound_ctrl:1
	v_fmamk_f32 v42, v42, 0x3c800000, v210
	v_rsq_f32_e32 v42, v42
	v_add_f32_dpp v43, v43, v43 row_mirror row_mask:0xf bank_mask:0xf bound_ctrl:1
	v_mov_b32_e32 v47, v43
	v_pk_add_f32 v[36:37], v[36:37], v[48:49] op_sel_hi:[1,0] neg_lo:[0,1] neg_hi:[0,1]
	v_add_f32_dpp v44, v44, v44 quad_perm:[2,3,0,1] row_mask:0xf bank_mask:0xf bound_ctrl:1
	v_permlane16_swap_b32_e32 v43, v47
	v_pk_mul_f32 v[48:49], v[36:37], v[36:37]
	v_add_f32_dpp v44, v44, v44 row_half_mirror row_mask:0xf bank_mask:0xf bound_ctrl:1
	v_add_f32_e32 v43, v43, v47
	v_add_f32_e32 v45, v48, v49
	v_add_f32_dpp v44, v44, v44 row_mirror row_mask:0xf bank_mask:0xf bound_ctrl:1
	v_fmamk_f32 v43, v43, 0x3c800000, v210
	v_mul_f32_e32 v35, v35, v42
	v_and_b32_e32 v31, 0xffff0000, v31
	v_add_f32_dpp v45, v45, v45 quad_perm:[1,0,3,2] row_mask:0xf bank_mask:0xf bound_ctrl:1
	v_mov_b32_e32 v48, v44
	v_rsq_f32_e32 v43, v43
	v_mul_f32_e32 v34, v34, v42
	v_fma_f32 v35, v3, v35, v11
	v_add_f32_dpp v45, v45, v45 quad_perm:[2,3,0,1] row_mask:0xf bank_mask:0xf bound_ctrl:1
	v_permlane16_swap_b32_e32 v44, v48
	v_fma_f32 v34, v2, v34, v10
	v_add_f32_e32 v31, v35, v31
	v_add_f32_dpp v45, v45, v45 row_half_mirror row_mask:0xf bank_mask:0xf bound_ctrl:1
	v_add_f32_e32 v44, v44, v48
	v_add_f32_e32 v34, v34, v50
	v_cvt_pk_bf16_f32 v31, v34, v31
	v_add_f32_dpp v45, v45, v45 row_mirror row_mask:0xf bank_mask:0xf bound_ctrl:1
	v_fmamk_f32 v44, v44, 0x3c800000, v210
	v_lshlrev_b32_e32 v34, 16, v31
	v_and_b32_e32 v31, 0xffff0000, v31
	v_mov_b32_e32 v49, v45
	v_rsq_f32_e32 v44, v44
	v_mul_f32_e32 v38, v38, v43
	v_mul_f32_e32 v39, v39, v43
	v_mul_f32_e32 v31, v52, v31
	v_permlane16_swap_b32_e32 v45, v49
	v_fma_f32 v38, v4, v38, v12
	v_fma_f32 v39, v5, v39, v13
	v_mul_f32_e32 v34, v51, v34
	v_cvt_pk_bf16_f32 v31, v34, v31
	v_add_f32_e32 v45, v45, v49
	v_add_f32_e32 v35, v38, v53
	v_add_f32_e32 v38, v39, v54
	global_store_dword v[32:33], v31, off
	v_cvt_pk_bf16_f32 v31, v35, v38
	v_fmamk_f32 v45, v45, 0x3c800000, v210
	v_lshlrev_b32_e32 v34, 16, v31
	v_and_b32_e32 v31, 0xffff0000, v31
	v_rsq_f32_e32 v45, v45
	v_mul_f32_e32 v40, v40, v44
	v_mul_f32_e32 v41, v41, v44
	v_mul_f32_e32 v31, v56, v31
	v_fma_f32 v40, v6, v40, v14
	v_fma_f32 v41, v7, v41, v15
	v_mul_f32_e32 v34, v55, v34
	v_cvt_pk_bf16_f32 v31, v34, v31
	v_add_f32_e32 v39, v40, v57
	v_add_f32_e32 v40, v41, v58
	global_store_dword v[32:33], v31, off offset:256
	v_cvt_pk_bf16_f32 v31, v39, v40
	v_mul_f32_e32 v36, v36, v45
	v_lshlrev_b32_e32 v34, 16, v31
	v_and_b32_e32 v31, 0xffff0000, v31
	v_mul_f32_e32 v37, v37, v45
	v_mul_f32_e32 v31, v60, v31
	v_fma_f32 v36, v8, v36, v16
	v_fma_f32 v37, v9, v37, v17
	v_mul_f32_e32 v34, v59, v34
	v_cvt_pk_bf16_f32 v31, v34, v31
	v_add_f32_e32 v36, v36, v61
	v_add_f32_e32 v37, v37, v62
	global_store_dword v[32:33], v31, off offset:512
	v_cvt_pk_bf16_f32 v31, v36, v37
	s_nop 0
	v_lshlrev_b32_e32 v34, 16, v31
	v_and_b32_e32 v31, 0xffff0000, v31
	v_mul_f32_e32 v31, v64, v31
	v_mul_f32_e32 v34, v63, v34
	v_cvt_pk_bf16_f32 v31, v34, v31
	global_store_dword v[32:33], v31, off offset:768
	s_andn2_b64 exec, exec, s[10:11]
	s_cbranch_execnz .LBB0_45

; DI unsigned cvtpk(float lo, float hi) { unsigned r; asm volatile("v_cvt_pk_bf16_f32 %0, %1, %2" : "=v"(r) : "v"(lo), "v"(hi)); return r; }
;     ...
; #pragma unroll
;         for (int k = 0; k < 2; ++k) {
;             const int r = r0 + k;
;             float ss = 0.f;
; #pragma unroll
;             for (int i = 0; i < 4; ++i) ss += v[k][i][0] * v[k][i][0] + v[k][i][1] * v[k][i][1] + v[k][i][2] * v[k][i][2] + v[k][i][3] * v[k][i][3];
;             ss = wave_sum(ss);
;             const float rstd = __builtin_amdgcn_rsqf(ss * (1.f / 1024.f) + 1e-6f);
;             if (mode == 2) {
; #pragma unroll
;                 for (int i = 0; i < 4; ++i) __builtin_nontemporal_store(v[k][i] * rstd * gv[i], (f32x4*)(xbuf + (size_t)r * DM + lane * 4 + 256 * i));
;             } else {
;                 const float* mr = modl + (size_t)modrow_of(r) * MOD_LD;
; #pragma unroll
;                 for (int i = 0; i < 4; ++i) {
;                     const int c = lane * 4 + 256 * i;
;                     const f32x4 sc = *(const f32x4*)(mr + sc_off + c), sh = *(const f32x4*)(mr + sh_off + c);
;                     const f32x4 y = v[k][i] * rstd * gv[i] * (sc + 1.f) + sh;
;                     u32x2 o; o[0] = cvtpk(y[0], y[1]); o[1] = cvtpk(y[2], y[3]);
;                     *(u32x2*)(h + (size_t)r * DM + c) = o;
;                     if (mode == 0) *(f32x4*)(xbuf + (size_t)r * DM + c) = v[k][i];
;                 }
.LBB0_64:
	s_or_b64 exec, exec, s[22:23]
	s_waitcnt vmcnt(7)
	v_mul_f32_e32 v61, v47, v47
	s_waitcnt vmcnt(6)
	v_mul_f32_e32 v63, v39, v39
	v_fmac_f32_e32 v61, v46, v46
	v_fmac_f32_e32 v63, v38, v38
	v_fmac_f32_e32 v61, v48, v48
	v_fmac_f32_e32 v63, v40, v40
	v_fmac_f32_e32 v61, v49, v49
	v_fmac_f32_e32 v63, v41, v41
	v_add_f32_e32 v61, v63, v61
	s_waitcnt vmcnt(5)
	v_mul_f32_e32 v63, v35, v35
	v_fmac_f32_e32 v63, v34, v34
	v_fmac_f32_e32 v63, v36, v36
	v_fmac_f32_e32 v63, v37, v37
	v_add_f32_e32 v61, v63, v61
	s_waitcnt vmcnt(4)
	v_mul_f32_e32 v63, v31, v31
	v_fmac_f32_e32 v63, v30, v30
	v_fmac_f32_e32 v63, v32, v32
	v_fmac_f32_e32 v63, v33, v33
	v_add_f32_e32 v61, v63, v61
	v_cmp_gt_i32_e32 vcc, s95, v66
	v_ashrrev_i32_e32 v73, 11, v66
	v_add_f32_dpp v61, v61, v61 quad_perm:[1,0,3,2] row_mask:0xf bank_mask:0xf bound_ctrl:1
	s_mov_b64 s[22:23], 0x4000
	s_mov_b64 s[30:31], 0x3000
	v_add_f32_dpp v61, v61, v61 quad_perm:[2,3,0,1] row_mask:0xf bank_mask:0xf bound_ctrl:1
	v_lshlrev_b64 v[86:87], 11, v[66:67]
	v_mov_b32_e32 v65, v1
	v_add_f32_dpp v61, v61, v61 row_half_mirror row_mask:0xf bank_mask:0xf bound_ctrl:1
	v_add_u32_e32 v50, s57, v50
	s_nop 0
	v_add_f32_dpp v61, v61, v61 row_mirror row_mask:0xf bank_mask:0xf bound_ctrl:1
	v_mov_b32_e32 v63, v61
	s_nop 1
	v_permlane16_swap_b32_e32 v61, v63
	v_add_f32_e32 v61, v61, v63
	v_mov_b32_e32 v63, v61
	s_nop 1
	v_permlane32_swap_b32_e32 v61, v63
	v_add_f32_e32 v61, v61, v63
	v_fmamk_f32 v61, v61, 0x3a800000, v211
	v_rsq_f32_e32 v72, v61
	v_lshrrev_b32_e32 v61, 5, v70
	v_add_u32_e32 v61, 16, v61
	v_cndmask_b32_e32 v61, v61, v73, vcc
	v_mov_b64_e32 v[70:71], s[8:9]
	v_mad_i64_i32 v[74:75], s[16:17], v61, s55, v[70:71]
	v_lshl_add_u64 v[76:77], v[74:75], 0, s[22:23]
	v_lshl_add_u64 v[74:75], v[74:75], 0, s[30:31]
	v_lshl_add_u64 v[78:79], v[76:77], 0, v[0:1]
	global_load_dwordx4 v[78:81], v[78:79], off
	v_lshl_add_u64 v[82:83], v[74:75], 0, v[0:1]
	global_load_dwordx4 v[82:85], v[82:83], off
	v_pk_mul_f32 v[46:47], v[46:47], v[72:73] op_sel_hi:[1,0]
	v_pk_mul_f32 v[48:49], v[48:49], v[72:73] op_sel_hi:[1,0]
	v_pk_mul_f32 v[46:47], v[2:3], v[46:47]
	v_pk_mul_f32 v[48:49], v[4:5], v[48:49]
	v_mov_b32_e32 v61, v1
	v_pk_mul_f32 v[38:39], v[38:39], v[72:73] op_sel_hi:[1,0]
	v_pk_mul_f32 v[40:41], v[40:41], v[72:73] op_sel_hi:[1,0]
	v_pk_mul_f32 v[38:39], v[6:7], v[38:39]
	v_pk_mul_f32 v[40:41], v[8:9], v[40:41]
	v_mov_b32_e32 v63, v1
	v_pk_mul_f32 v[34:35], v[34:35], v[72:73] op_sel_hi:[1,0]
	v_pk_mul_f32 v[36:37], v[36:37], v[72:73] op_sel_hi:[1,0]
	v_pk_mul_f32 v[34:35], v[10:11], v[34:35]
	v_pk_mul_f32 v[36:37], v[12:13], v[36:37]
	v_pk_mul_f32 v[30:31], v[30:31], v[72:73] op_sel_hi:[1,0]
	v_pk_mul_f32 v[32:33], v[32:33], v[72:73] op_sel_hi:[1,0]
	v_pk_mul_f32 v[30:31], v[14:15], v[30:31]
	v_pk_mul_f32 v[32:33], v[16:17], v[32:33]
	v_cmp_gt_i32_e32 vcc, s96, v66
	s_waitcnt vmcnt(1)
	v_pk_add_f32 v[78:79], v[78:79], 1.0 op_sel_hi:[1,0]
	v_pk_add_f32 v[80:81], v[80:81], 1.0 op_sel_hi:[1,0]
	s_waitcnt vmcnt(0)
	v_pk_fma_f32 v[46:47], v[78:79], v[46:47], v[82:83]
	v_pk_fma_f32 v[48:49], v[80:81], v[48:49], v[84:85]
	v_cvt_pk_bf16_f32 v78, v46, v47
	v_lshl_add_u64 v[46:47], v[58:59], 0, v[86:87]
	v_cvt_pk_bf16_f32 v79, v48, v49
	global_store_dwordx2 v[46:47], v[78:79], off
	v_lshl_add_u64 v[48:49], v[76:77], 0, v[60:61]
	global_load_dwordx4 v[78:81], v[48:49], off
	v_lshl_add_u64 v[48:49], v[74:75], 0, v[60:61]
	global_load_dwordx4 v[82:85], v[48:49], off
	s_waitcnt vmcnt(1)
	v_pk_add_f32 v[78:79], v[78:79], 1.0 op_sel_hi:[1,0]
	v_pk_add_f32 v[48:49], v[80:81], 1.0 op_sel_hi:[1,0]
	s_waitcnt vmcnt(0)
	v_pk_fma_f32 v[38:39], v[78:79], v[38:39], v[82:83]
	v_pk_fma_f32 v[40:41], v[48:49], v[40:41], v[84:85]
	v_cvt_pk_bf16_f32 v38, v38, v39
	v_lshl_add_u64 v[48:49], v[74:75], 0, v[62:63]
	v_cvt_pk_bf16_f32 v39, v40, v41
	global_store_dwordx2 v[46:47], v[38:39], off offset:512
	v_lshl_add_u64 v[38:39], v[76:77], 0, v[62:63]
	global_load_dwordx4 v[38:41], v[38:39], off
	s_nop 0
	global_load_dwordx4 v[78:81], v[48:49], off
	s_waitcnt vmcnt(1)
	v_pk_add_f32 v[38:39], v[38:39], 1.0 op_sel_hi:[1,0]
	v_pk_add_f32 v[40:41], v[40:41], 1.0 op_sel_hi:[1,0]
	s_waitcnt vmcnt(0)
	v_pk_fma_f32 v[34:35], v[34:35], v[38:39], v[78:79]
	v_pk_fma_f32 v[36:37], v[36:37], v[40:41], v[80:81]
	v_cvt_pk_bf16_f32 v34, v34, v35
	v_lshl_add_u64 v[38:39], v[74:75], 0, v[64:65]
	v_cvt_pk_bf16_f32 v35, v36, v37
	global_store_dwordx2 v[46:47], v[34:35], off offset:1024
	v_lshl_add_u64 v[34:35], v[76:77], 0, v[64:65]
	global_load_dwordx4 v[34:37], v[34:35], off
	s_nop 0
	global_load_dwordx4 v[38:41], v[38:39], off
	s_waitcnt vmcnt(1)
	v_pk_add_f32 v[34:35], v[34:35], 1.0 op_sel_hi:[1,0]
	v_pk_add_f32 v[36:37], v[36:37], 1.0 op_sel_hi:[1,0]
	s_waitcnt vmcnt(0)
; DI unsigned cvtpk(float lo, float hi) { unsigned r; asm volatile("v_cvt_pk_bf16_f32 %0, %1, %2" : "=v"(r) : "v"(lo), "v"(hi)); return r; }
;     ...
;         for (int k = 0; k < 2; ++k) {
;             const int r = r0 + k;
;             float ss = 0.f;
; #pragma unroll
;             for (int i = 0; i < 4; ++i) ss += v[k][i][0] * v[k][i][0] + v[k][i][1] * v[k][i][1] + v[k][i][2] * v[k][i][2] + v[k][i][3] * v[k][i][3];
;             ss = wave_sum(ss);
;             const float rstd = __builtin_amdgcn_rsqf(ss * (1.f / 1024.f) + 1e-6f);
;             if (mode == 2) {
; #pragma unroll
;                 for (int i = 0; i < 4; ++i) __builtin_nontemporal_store(v[k][i] * rstd * gv[i], (f32x4*)(xbuf + (size_t)r * DM + lane * 4 + 256 * i));
;             } else {
;                 const float* mr = modl + (size_t)modrow_of(r) * MOD_LD;
; #pragma unroll
;                 for (int i = 0; i < 4; ++i) {
;                     const int c = lane * 4 + 256 * i;
;                     const f32x4 sc = *(const f32x4*)(mr + sc_off + c), sh = *(const f32x4*)(mr + sh_off + c);
;                     const f32x4 y = v[k][i] * rstd * gv[i] * (sc + 1.f) + sh;
;                     u32x2 o; o[0] = cvtpk(y[0], y[1]); o[1] = cvtpk(y[2], y[3]);
;                     *(u32x2*)(h + (size_t)r * DM + c) = o;
;                     if (mode == 0) *(f32x4*)(xbuf + (size_t)r * DM + c) = v[k][i];
;                 }
	v_pk_fma_f32 v[30:31], v[30:31], v[34:35], v[38:39]
	v_pk_fma_f32 v[32:33], v[32:33], v[36:37], v[40:41]
	v_cvt_pk_bf16_f32 v30, v30, v31
	v_lshlrev_b64 v[40:41], 11, v[68:69]
	v_cvt_pk_bf16_f32 v31, v32, v33
	global_store_dwordx2 v[46:47], v[30:31], off offset:1536
	v_mul_f32_e32 v30, v43, v43
	v_mul_f32_e32 v31, v27, v27
	v_fmac_f32_e32 v30, v42, v42
	v_fmac_f32_e32 v31, v26, v26
	v_fmac_f32_e32 v30, v44, v44
	v_fmac_f32_e32 v31, v28, v28
	v_fmac_f32_e32 v30, v45, v45
	v_fmac_f32_e32 v31, v29, v29
	v_add_f32_e32 v30, v31, v30
	v_mul_f32_e32 v31, v23, v23
	v_fmac_f32_e32 v31, v22, v22
	v_fmac_f32_e32 v31, v24, v24
	v_fmac_f32_e32 v31, v25, v25
	v_add_f32_e32 v30, v31, v30
	v_mul_f32_e32 v31, v19, v19
	v_fmac_f32_e32 v31, v18, v18
	v_fmac_f32_e32 v31, v20, v20
	v_fmac_f32_e32 v31, v21, v21
	v_add_f32_e32 v30, v31, v30
	s_nop 1
	v_add_f32_dpp v30, v30, v30 quad_perm:[1,0,3,2] row_mask:0xf bank_mask:0xf bound_ctrl:1
	s_nop 1
	v_add_f32_dpp v30, v30, v30 quad_perm:[2,3,0,1] row_mask:0xf bank_mask:0xf bound_ctrl:1
	s_nop 1
	v_add_f32_dpp v30, v30, v30 row_half_mirror row_mask:0xf bank_mask:0xf bound_ctrl:1
	s_nop 1
	v_add_f32_dpp v30, v30, v30 row_mirror row_mask:0xf bank_mask:0xf bound_ctrl:1
	v_mov_b32_e32 v31, v30
	s_nop 1
	v_permlane16_swap_b32_e32 v30, v31
	v_add_f32_e32 v30, v30, v31
	v_mov_b32_e32 v31, v30
	s_nop 1
	v_permlane32_swap_b32_e32 v30, v31
	v_add_f32_e32 v30, v30, v31
	v_cndmask_b32_e32 v31, v51, v73, vcc
	v_mad_i64_i32 v[32:33], s[16:17], v31, s55, v[70:71]
	v_lshl_add_u64 v[34:35], v[32:33], 0, s[22:23]
	v_lshl_add_u64 v[32:33], v[32:33], 0, s[30:31]
	v_lshl_add_u64 v[36:37], v[34:35], 0, v[0:1]
	global_load_dwordx4 v[36:39], v[36:37], off
	v_lshl_add_u64 v[46:47], v[32:33], 0, v[0:1]
	global_load_dwordx4 v[46:49], v[46:47], off
	v_fmamk_f32 v30, v30, 0x3a800000, v211
	v_rsq_f32_e32 v30, v30
	v_cmp_lt_i32_e32 vcc, s59, v50
	s_or_b64 s[10:11], vcc, s[10:11]
	v_pk_mul_f32 v[42:43], v[42:43], v[30:31] op_sel_hi:[1,0]
	v_pk_mul_f32 v[44:45], v[44:45], v[30:31] op_sel_hi:[1,0]
	v_pk_mul_f32 v[42:43], v[2:3], v[42:43]
	v_pk_mul_f32 v[44:45], v[4:5], v[44:45]
	v_pk_mul_f32 v[26:27], v[26:27], v[30:31] op_sel_hi:[1,0]
	v_pk_mul_f32 v[28:29], v[28:29], v[30:31] op_sel_hi:[1,0]
	v_pk_mul_f32 v[26:27], v[6:7], v[26:27]
	v_pk_mul_f32 v[28:29], v[8:9], v[28:29]
	v_pk_mul_f32 v[22:23], v[22:23], v[30:31] op_sel_hi:[1,0]
	v_pk_mul_f32 v[24:25], v[24:25], v[30:31] op_sel_hi:[1,0]
	v_pk_mul_f32 v[22:23], v[10:11], v[22:23]
	v_pk_mul_f32 v[24:25], v[12:13], v[24:25]
	v_pk_mul_f32 v[18:19], v[18:19], v[30:31] op_sel_hi:[1,0]
	v_pk_mul_f32 v[20:21], v[20:21], v[30:31] op_sel_hi:[1,0]
	v_pk_mul_f32 v[18:19], v[14:15], v[18:19]
	v_pk_mul_f32 v[20:21], v[16:17], v[20:21]
	s_waitcnt vmcnt(1)
	v_pk_add_f32 v[36:37], v[36:37], 1.0 op_sel_hi:[1,0]
	v_pk_add_f32 v[38:39], v[38:39], 1.0 op_sel_hi:[1,0]
	s_waitcnt vmcnt(0)
	v_pk_fma_f32 v[36:37], v[36:37], v[42:43], v[46:47]
	v_pk_fma_f32 v[38:39], v[38:39], v[44:45], v[48:49]
	v_cvt_pk_bf16_f32 v42, v36, v37
	v_lshl_add_u64 v[36:37], v[58:59], 0, v[40:41]
	v_cvt_pk_bf16_f32 v43, v38, v39
	global_store_dwordx2 v[36:37], v[42:43], off
	v_lshl_add_u64 v[38:39], v[34:35], 0, v[60:61]
	global_load_dwordx4 v[38:41], v[38:39], off
	v_lshl_add_u64 v[42:43], v[32:33], 0, v[60:61]
	global_load_dwordx4 v[42:45], v[42:43], off
	s_waitcnt vmcnt(1)
	v_pk_add_f32 v[38:39], v[38:39], 1.0 op_sel_hi:[1,0]
	v_pk_add_f32 v[40:41], v[40:41], 1.0 op_sel_hi:[1,0]
	s_waitcnt vmcnt(0)
	v_pk_fma_f32 v[26:27], v[38:39], v[26:27], v[42:43]
	v_pk_fma_f32 v[28:29], v[40:41], v[28:29], v[44:45]
	v_cvt_pk_bf16_f32 v26, v26, v27
	v_lshl_add_u64 v[38:39], v[32:33], 0, v[62:63]
	v_cvt_pk_bf16_f32 v27, v28, v29
	global_store_dwordx2 v[36:37], v[26:27], off offset:512
	v_lshl_add_u64 v[26:27], v[34:35], 0, v[62:63]
	global_load_dwordx4 v[26:29], v[26:27], off
	s_nop 0
	global_load_dwordx4 v[38:41], v[38:39], off
	s_waitcnt vmcnt(1)
	v_pk_add_f32 v[26:27], v[26:27], 1.0 op_sel_hi:[1,0]
	v_pk_add_f32 v[28:29], v[28:29], 1.0 op_sel_hi:[1,0]
	s_waitcnt vmcnt(0)
	v_pk_fma_f32 v[22:23], v[22:23], v[26:27], v[38:39]
	v_pk_fma_f32 v[24:25], v[24:25], v[28:29], v[40:41]
	v_cvt_pk_bf16_f32 v22, v22, v23
	v_lshl_add_u64 v[26:27], v[32:33], 0, v[64:65]
	v_cvt_pk_bf16_f32 v23, v24, v25
	global_store_dwordx2 v[36:37], v[22:23], off offset:1024
	v_lshl_add_u64 v[22:23], v[34:35], 0, v[64:65]
	global_load_dwordx4 v[22:25], v[22:23], off
	s_nop 0
	global_load_dwordx4 v[26:29], v[26:27], off
	s_waitcnt vmcnt(1)
	v_pk_add_f32 v[22:23], v[22:23], 1.0 op_sel_hi:[1,0]
	v_pk_add_f32 v[24:25], v[24:25], 1.0 op_sel_hi:[1,0]
	s_waitcnt vmcnt(0)
	v_pk_fma_f32 v[18:19], v[18:19], v[22:23], v[26:27]
	v_pk_fma_f32 v[20:21], v[20:21], v[24:25], v[28:29]
	v_cvt_pk_bf16_f32 v18, v18, v19
	s_nop 0
	v_cvt_pk_bf16_f32 v19, v20, v21
	global_store_dwordx2 v[36:37], v[18:19], off offset:1536
	s_andn2_b64 exec, exec, s[10:11]
	s_cbranch_execz .LBB0_130

;     ...
; #pragma unroll
;         for (int k = 0; k < 2; ++k) {
;             const int r = r0 + k;
;             float ss = 0.f;
; #pragma unroll
;             for (int i = 0; i < 4; ++i) ss += v[k][i][0] * v[k][i][0] + v[k][i][1] * v[k][i][1] + v[k][i][2] * v[k][i][2] + v[k][i][3] * v[k][i][3];
;             ss = wave_sum(ss);
;             const float rstd = __builtin_amdgcn_rsqf(ss * (1.f / 1024.f) + 1e-6f);
;             if (mode == 2) {
; #pragma unroll
;                 for (int i = 0; i < 4; ++i) __builtin_nontemporal_store(v[k][i] * rstd * gv[i], (f32x4*)(xbuf + (size_t)r * DM + lane * 4 + 256 * i));
.LBB0_171:
	s_or_b64 exec, exec, s[10:11]
	s_waitcnt vmcnt(7)
	v_mul_f32_e32 v0, v31, v31
	s_waitcnt vmcnt(6)
	v_mul_f32_e32 v50, v27, v27
	v_fmac_f32_e32 v0, v30, v30
	v_fmac_f32_e32 v50, v26, v26
	v_fmac_f32_e32 v0, v32, v32
	v_fmac_f32_e32 v50, v28, v28
	v_fmac_f32_e32 v0, v33, v33
	v_fmac_f32_e32 v50, v29, v29
	v_add_f32_e32 v0, v50, v0
	s_waitcnt vmcnt(5)
	v_mul_f32_e32 v50, v23, v23
	v_fmac_f32_e32 v50, v22, v22
	v_fmac_f32_e32 v50, v24, v24
	v_fmac_f32_e32 v50, v25, v25
	v_add_f32_e32 v0, v50, v0
	s_waitcnt vmcnt(4)
	v_mul_f32_e32 v50, v19, v19
	v_fmac_f32_e32 v50, v18, v18
	v_fmac_f32_e32 v50, v20, v20
	v_fmac_f32_e32 v50, v21, v21
	v_add_f32_e32 v0, v50, v0
	v_add_u32_e32 v54, s57, v54
	v_cmp_lt_i32_e32 vcc, s59, v54
	v_add_f32_dpp v0, v0, v0 quad_perm:[1,0,3,2] row_mask:0xf bank_mask:0xf bound_ctrl:1
	s_or_b64 s[8:9], vcc, s[8:9]
	s_nop 0
	v_add_f32_dpp v0, v0, v0 quad_perm:[2,3,0,1] row_mask:0xf bank_mask:0xf bound_ctrl:1
	s_nop 1
	v_add_f32_dpp v0, v0, v0 row_half_mirror row_mask:0xf bank_mask:0xf bound_ctrl:1
	s_nop 1
	v_add_f32_dpp v0, v0, v0 row_mirror row_mask:0xf bank_mask:0xf bound_ctrl:1
	v_mov_b32_e32 v50, v0
	s_nop 1
	v_permlane16_swap_b32_e32 v0, v50
	v_add_f32_e32 v0, v0, v50
	v_mov_b32_e32 v50, v0
	s_nop 1
	v_permlane32_swap_b32_e32 v0, v50
	v_add_f32_e32 v0, v0, v50
	v_fmamk_f32 v0, v0, 0x3a800000, v211
	v_rsq_f32_e32 v0, v0
	s_nop 0
	v_pk_mul_f32 v[22:23], v[22:23], v[0:1] op_sel_hi:[1,0]
	v_pk_mul_f32 v[24:25], v[24:25], v[0:1] op_sel_hi:[1,0]
	v_pk_mul_f32 v[22:23], v[10:11], v[22:23]
	v_pk_mul_f32 v[24:25], v[12:13], v[24:25]
	v_pk_mul_f32 v[30:31], v[30:31], v[0:1] op_sel_hi:[1,0]
	v_pk_mul_f32 v[32:33], v[32:33], v[0:1] op_sel_hi:[1,0]
	v_pk_mul_f32 v[26:27], v[26:27], v[0:1] op_sel_hi:[1,0]
	v_pk_mul_f32 v[28:29], v[28:29], v[0:1] op_sel_hi:[1,0]
	global_store_dwordx4 v[62:63], v[22:25], off offset:2048 nt
	v_pk_mul_f32 v[18:19], v[18:19], v[0:1] op_sel_hi:[1,0]
	v_pk_mul_f32 v[20:21], v[20:21], v[0:1] op_sel_hi:[1,0]
	s_waitcnt vmcnt(4)
	v_mul_f32_e32 v0, v47, v47
	s_waitcnt vmcnt(3)
	v_mul_f32_e32 v22, v43, v43
	v_fmac_f32_e32 v0, v46, v46
	v_fmac_f32_e32 v22, v42, v42
	v_fmac_f32_e32 v0, v48, v48
	v_fmac_f32_e32 v22, v44, v44
	v_fmac_f32_e32 v0, v49, v49
	v_fmac_f32_e32 v22, v45, v45
	v_add_f32_e32 v0, v22, v0
	s_waitcnt vmcnt(2)
	v_mul_f32_e32 v22, v39, v39
	v_fmac_f32_e32 v22, v38, v38
	v_fmac_f32_e32 v22, v40, v40
	v_fmac_f32_e32 v22, v41, v41
	v_add_f32_e32 v0, v22, v0
	s_waitcnt vmcnt(1)
	v_mul_f32_e32 v22, v35, v35
	v_fmac_f32_e32 v22, v34, v34
	v_fmac_f32_e32 v22, v36, v36
	v_fmac_f32_e32 v22, v37, v37
	v_add_f32_e32 v0, v22, v0
	v_pk_mul_f32 v[20:21], v[16:17], v[20:21]
	v_pk_mul_f32 v[18:19], v[14:15], v[18:19]
	v_add_f32_dpp v0, v0, v0 quad_perm:[1,0,3,2] row_mask:0xf bank_mask:0xf bound_ctrl:1
	global_store_dwordx4 v[62:63], v[18:21], off offset:3072 nt
	v_pk_mul_f32 v[32:33], v[4:5], v[32:33]
	v_add_f32_dpp v0, v0, v0 quad_perm:[2,3,0,1] row_mask:0xf bank_mask:0xf bound_ctrl:1
	v_pk_mul_f32 v[30:31], v[2:3], v[30:31]
	v_pk_mul_f32 v[28:29], v[8:9], v[28:29]
	v_add_f32_dpp v0, v0, v0 row_half_mirror row_mask:0xf bank_mask:0xf bound_ctrl:1
	v_pk_mul_f32 v[26:27], v[6:7], v[26:27]
	global_store_dwordx4 v[62:63], v[30:33], off nt
	v_add_f32_dpp v0, v0, v0 row_mirror row_mask:0xf bank_mask:0xf bound_ctrl:1
	v_mov_b32_e32 v22, v0
	s_nop 1
	v_permlane16_swap_b32_e32 v0, v22
	v_add_f32_e32 v0, v0, v22
	v_mov_b32_e32 v22, v0
	s_nop 1
	v_permlane32_swap_b32_e32 v0, v22
	v_add_f32_e32 v0, v0, v22
	v_fmamk_f32 v0, v0, 0x3a800000, v211
	v_rsq_f32_e32 v0, v0
	global_store_dwordx4 v[62:63], v[26:29], off offset:1024 nt
	v_pk_mul_f32 v[18:19], v[46:47], v[0:1] op_sel_hi:[1,0]
	v_pk_mul_f32 v[20:21], v[48:49], v[0:1] op_sel_hi:[1,0]
	v_pk_mul_f32 v[18:19], v[2:3], v[18:19]
	v_pk_mul_f32 v[20:21], v[4:5], v[20:21]
	global_store_dwordx4 v[64:65], v[18:21], off nt
	s_nop 1
	v_pk_mul_f32 v[18:19], v[42:43], v[0:1] op_sel_hi:[1,0]
	v_pk_mul_f32 v[20:21], v[44:45], v[0:1] op_sel_hi:[1,0]
	v_pk_mul_f32 v[18:19], v[6:7], v[18:19]
	v_pk_mul_f32 v[20:21], v[8:9], v[20:21]
	global_store_dwordx4 v[64:65], v[18:21], off offset:1024 nt
	s_nop 1
	v_pk_mul_f32 v[18:19], v[38:39], v[0:1] op_sel_hi:[1,0]
	v_pk_mul_f32 v[20:21], v[40:41], v[0:1] op_sel_hi:[1,0]
	v_pk_mul_f32 v[18:19], v[10:11], v[18:19]
	v_pk_mul_f32 v[20:21], v[12:13], v[20:21]
	global_store_dwordx4 v[64:65], v[18:21], off offset:2048 nt
	s_nop 1
	v_pk_mul_f32 v[18:19], v[34:35], v[0:1] op_sel_hi:[1,0]
	v_pk_mul_f32 v[20:21], v[36:37], v[0:1] op_sel_hi:[1,0]
	v_pk_mul_f32 v[18:19], v[14:15], v[18:19]
	v_pk_mul_f32 v[20:21], v[16:17], v[20:21]
	global_store_dwordx4 v[64:65], v[18:21], off offset:3072 nt
	s_andn2_b64 exec, exec, s[8:9]
	s_cbranch_execz .LBB0_176

; DI unsigned cvtpk(float lo, float hi) { unsigned r; asm volatile("v_cvt_pk_bf16_f32 %0, %1, %2" : "=v"(r) : "v"(lo), "v"(hi)); return r; }
;     ...
; #pragma unroll
;         for (int k = 0; k < 2; ++k) {
;             const int r = r0 + k;
;             float ss = 0.f;
; #pragma unroll
;             for (int i = 0; i < 4; ++i) ss += v[k][i][0] * v[k][i][0] + v[k][i][1] * v[k][i][1] + v[k][i][2] * v[k][i][2] + v[k][i][3] * v[k][i][3];
;             ss = wave_sum(ss);
;             const float rstd = __builtin_amdgcn_rsqf(ss * (1.f / 1024.f) + 1e-6f);
;             if (mode == 2) {
; #pragma unroll
;                 for (int i = 0; i < 4; ++i) __builtin_nontemporal_store(v[k][i] * rstd * gv[i], (f32x4*)(xbuf + (size_t)r * DM + lane * 4 + 256 * i));
;             } else {
;                 const float* mr = modl + (size_t)modrow_of(r) * MOD_LD;
; #pragma unroll
;                 for (int i = 0; i < 4; ++i) {
;                     const int c = lane * 4 + 256 * i;
;                     const f32x4 sc = *(const f32x4*)(mr + sc_off + c), sh = *(const f32x4*)(mr + sh_off + c);
;                     const f32x4 y = v[k][i] * rstd * gv[i] * (sc + 1.f) + sh;
;                     u32x2 o; o[0] = cvtpk(y[0], y[1]); o[1] = cvtpk(y[2], y[3]);
;                     *(u32x2*)(h + (size_t)r * DM + c) = o;
;                     if (mode == 0) *(f32x4*)(xbuf + (size_t)r * DM + c) = v[k][i];
;                 }
.LBB0_180:
	s_or_b64 exec, exec, s[22:23]
	s_waitcnt vmcnt(7)
	v_mul_f32_e32 v61, v31, v31
	s_waitcnt vmcnt(6)
	v_mul_f32_e32 v63, v27, v27
	v_fmac_f32_e32 v61, v30, v30
	v_fmac_f32_e32 v63, v26, v26
	v_fmac_f32_e32 v61, v32, v32
	v_fmac_f32_e32 v63, v28, v28
	v_fmac_f32_e32 v61, v33, v33
	v_fmac_f32_e32 v63, v29, v29
	v_add_f32_e32 v61, v63, v61
	s_waitcnt vmcnt(5)
	v_mul_f32_e32 v63, v23, v23
	v_fmac_f32_e32 v63, v22, v22
	v_fmac_f32_e32 v63, v24, v24
	v_fmac_f32_e32 v63, v25, v25
	v_add_f32_e32 v61, v63, v61
	s_waitcnt vmcnt(4)
	v_mul_f32_e32 v63, v19, v19
	v_fmac_f32_e32 v63, v18, v18
	v_fmac_f32_e32 v63, v20, v20
	v_fmac_f32_e32 v63, v21, v21
	v_add_f32_e32 v61, v63, v61
	v_cmp_gt_i32_e32 vcc, s95, v66
	v_ashrrev_i32_e32 v73, 11, v66
	v_add_f32_dpp v61, v61, v61 quad_perm:[1,0,3,2] row_mask:0xf bank_mask:0xf bound_ctrl:1
	v_lshlrev_b64 v[86:87], 11, v[66:67]
	v_mov_b32_e32 v65, v1
	v_add_f32_dpp v61, v61, v61 quad_perm:[2,3,0,1] row_mask:0xf bank_mask:0xf bound_ctrl:1
	v_add_u32_e32 v50, s57, v50
	s_nop 0
	v_add_f32_dpp v61, v61, v61 row_half_mirror row_mask:0xf bank_mask:0xf bound_ctrl:1
	s_nop 1
	v_add_f32_dpp v61, v61, v61 row_mirror row_mask:0xf bank_mask:0xf bound_ctrl:1
	v_mov_b32_e32 v63, v61
	s_nop 1
	v_permlane16_swap_b32_e32 v61, v63
	v_add_f32_e32 v61, v61, v63
	v_mov_b32_e32 v63, v61
	s_nop 1
	v_permlane32_swap_b32_e32 v61, v63
	v_add_f32_e32 v61, v61, v63
	v_fmamk_f32 v61, v61, 0x3a800000, v211
	v_rsq_f32_e32 v72, v61
	v_lshrrev_b32_e32 v61, 5, v68
	v_add_u32_e32 v61, 16, v61
	v_cndmask_b32_e32 v61, v61, v73, vcc
	v_mov_b64_e32 v[68:69], s[12:13]
	v_mad_i64_i32 v[74:75], s[16:17], v61, s55, v[68:69]
	v_lshl_add_u64 v[76:77], v[74:75], 0, s[34:35]
	v_lshl_add_u64 v[78:79], v[76:77], 0, v[0:1]
	global_load_dwordx4 v[78:81], v[78:79], off
	v_lshl_add_u64 v[74:75], v[74:75], 0, v[0:1]
	global_load_dwordx4 v[82:85], v[74:75], off
	v_pk_mul_f32 v[30:31], v[30:31], v[72:73] op_sel_hi:[1,0]
	v_pk_mul_f32 v[32:33], v[32:33], v[72:73] op_sel_hi:[1,0]
	v_pk_mul_f32 v[30:31], v[2:3], v[30:31]
	v_pk_mul_f32 v[32:33], v[4:5], v[32:33]
	v_mov_b32_e32 v61, v1
	v_pk_mul_f32 v[26:27], v[26:27], v[72:73] op_sel_hi:[1,0]
	v_pk_mul_f32 v[28:29], v[28:29], v[72:73] op_sel_hi:[1,0]
	v_pk_mul_f32 v[26:27], v[6:7], v[26:27]
	v_pk_mul_f32 v[28:29], v[8:9], v[28:29]
	v_mov_b32_e32 v63, v1
	v_pk_mul_f32 v[22:23], v[22:23], v[72:73] op_sel_hi:[1,0]
	v_pk_mul_f32 v[24:25], v[24:25], v[72:73] op_sel_hi:[1,0]
	v_pk_mul_f32 v[22:23], v[10:11], v[22:23]
	v_pk_mul_f32 v[24:25], v[12:13], v[24:25]
	v_pk_mul_f32 v[18:19], v[18:19], v[72:73] op_sel_hi:[1,0]
	v_pk_mul_f32 v[20:21], v[20:21], v[72:73] op_sel_hi:[1,0]
	v_pk_mul_f32 v[18:19], v[14:15], v[18:19]
	v_pk_mul_f32 v[20:21], v[16:17], v[20:21]
	v_cmp_gt_i32_e32 vcc, s96, v66
	s_waitcnt vmcnt(1)
	v_pk_add_f32 v[78:79], v[78:79], 1.0 op_sel_hi:[1,0]
	v_pk_add_f32 v[80:81], v[80:81], 1.0 op_sel_hi:[1,0]
	s_waitcnt vmcnt(0)
	v_pk_fma_f32 v[30:31], v[78:79], v[30:31], v[82:83]
	v_pk_fma_f32 v[32:33], v[80:81], v[32:33], v[84:85]
	v_cvt_pk_bf16_f32 v78, v30, v31
	v_lshl_add_u64 v[30:31], v[58:59], 0, v[86:87]
	v_cvt_pk_bf16_f32 v79, v32, v33
	global_store_dwordx2 v[30:31], v[78:79], off
	v_lshl_add_u64 v[32:33], v[76:77], 0, v[60:61]
	global_load_dwordx4 v[78:81], v[32:33], off
	global_load_dwordx4 v[82:85], v[74:75], off offset:1024
	s_waitcnt vmcnt(1)
	v_pk_add_f32 v[78:79], v[78:79], 1.0 op_sel_hi:[1,0]
	v_pk_add_f32 v[32:33], v[80:81], 1.0 op_sel_hi:[1,0]
	s_waitcnt vmcnt(0)
	v_pk_fma_f32 v[26:27], v[78:79], v[26:27], v[82:83]
	v_pk_fma_f32 v[28:29], v[32:33], v[28:29], v[84:85]
	v_cvt_pk_bf16_f32 v26, v26, v27
	v_lshlrev_b64 v[32:33], 11, v[70:71]
	v_cvt_pk_bf16_f32 v27, v28, v29
	global_store_dwordx2 v[30:31], v[26:27], off offset:512
	v_lshl_add_u64 v[26:27], v[76:77], 0, v[62:63]
	global_load_dwordx4 v[26:29], v[26:27], off
	s_nop 0
	global_load_dwordx4 v[78:81], v[74:75], off offset:2048
	s_waitcnt vmcnt(1)
	v_pk_add_f32 v[26:27], v[26:27], 1.0 op_sel_hi:[1,0]
	v_pk_add_f32 v[28:29], v[28:29], 1.0 op_sel_hi:[1,0]
	s_waitcnt vmcnt(0)
	v_pk_fma_f32 v[22:23], v[22:23], v[26:27], v[78:79]
	v_pk_fma_f32 v[24:25], v[24:25], v[28:29], v[80:81]
	v_cvt_pk_bf16_f32 v22, v22, v23
	s_nop 0
	v_cvt_pk_bf16_f32 v23, v24, v25
	global_store_dwordx2 v[30:31], v[22:23], off offset:1024
	v_lshl_add_u64 v[22:23], v[76:77], 0, v[64:65]
	global_load_dwordx4 v[22:25], v[22:23], off
	s_nop 0
	global_load_dwordx4 v[26:29], v[74:75], off offset:3072
	s_waitcnt vmcnt(1)
	v_pk_add_f32 v[22:23], v[22:23], 1.0 op_sel_hi:[1,0]
	v_pk_add_f32 v[24:25], v[24:25], 1.0 op_sel_hi:[1,0]
	s_waitcnt vmcnt(0)
; DI unsigned cvtpk(float lo, float hi) { unsigned r; asm volatile("v_cvt_pk_bf16_f32 %0, %1, %2" : "=v"(r) : "v"(lo), "v"(hi)); return r; }
;     ...
;         for (int k = 0; k < 2; ++k) {
;             const int r = r0 + k;
;             float ss = 0.f;
; #pragma unroll
;             for (int i = 0; i < 4; ++i) ss += v[k][i][0] * v[k][i][0] + v[k][i][1] * v[k][i][1] + v[k][i][2] * v[k][i][2] + v[k][i][3] * v[k][i][3];
;             ss = wave_sum(ss);
;             const float rstd = __builtin_amdgcn_rsqf(ss * (1.f / 1024.f) + 1e-6f);
;             if (mode == 2) {
; #pragma unroll
;                 for (int i = 0; i < 4; ++i) __builtin_nontemporal_store(v[k][i] * rstd * gv[i], (f32x4*)(xbuf + (size_t)r * DM + lane * 4 + 256 * i));
;             } else {
;                 const float* mr = modl + (size_t)modrow_of(r) * MOD_LD;
; #pragma unroll
;                 for (int i = 0; i < 4; ++i) {
;                     const int c = lane * 4 + 256 * i;
;                     const f32x4 sc = *(const f32x4*)(mr + sc_off + c), sh = *(const f32x4*)(mr + sh_off + c);
;                     const f32x4 y = v[k][i] * rstd * gv[i] * (sc + 1.f) + sh;
;                     u32x2 o; o[0] = cvtpk(y[0], y[1]); o[1] = cvtpk(y[2], y[3]);
;                     *(u32x2*)(h + (size_t)r * DM + c) = o;
;                     if (mode == 0) *(f32x4*)(xbuf + (size_t)r * DM + c) = v[k][i];
;                 }
	v_pk_fma_f32 v[18:19], v[18:19], v[22:23], v[26:27]
	v_pk_fma_f32 v[20:21], v[20:21], v[24:25], v[28:29]
	v_cvt_pk_bf16_f32 v18, v18, v19
	s_nop 0
	v_cvt_pk_bf16_f32 v19, v20, v21
	global_store_dwordx2 v[30:31], v[18:19], off offset:1536
	v_mul_f32_e32 v18, v47, v47
	v_mul_f32_e32 v19, v43, v43
	v_fmac_f32_e32 v18, v46, v46
	v_fmac_f32_e32 v19, v42, v42
	v_fmac_f32_e32 v18, v48, v48
	v_fmac_f32_e32 v19, v44, v44
	v_fmac_f32_e32 v18, v49, v49
	v_fmac_f32_e32 v19, v45, v45
	v_add_f32_e32 v18, v19, v18
	v_mul_f32_e32 v19, v39, v39
	v_fmac_f32_e32 v19, v38, v38
	v_fmac_f32_e32 v19, v40, v40
	v_fmac_f32_e32 v19, v41, v41
	v_add_f32_e32 v18, v19, v18
	v_mul_f32_e32 v19, v35, v35
	v_fmac_f32_e32 v19, v34, v34
	v_fmac_f32_e32 v19, v36, v36
	v_fmac_f32_e32 v19, v37, v37
	v_add_f32_e32 v18, v19, v18
	s_nop 1
	v_add_f32_dpp v18, v18, v18 quad_perm:[1,0,3,2] row_mask:0xf bank_mask:0xf bound_ctrl:1
	s_nop 1
	v_add_f32_dpp v18, v18, v18 quad_perm:[2,3,0,1] row_mask:0xf bank_mask:0xf bound_ctrl:1
	s_nop 1
	v_add_f32_dpp v18, v18, v18 row_half_mirror row_mask:0xf bank_mask:0xf bound_ctrl:1
	s_nop 1
	v_add_f32_dpp v18, v18, v18 row_mirror row_mask:0xf bank_mask:0xf bound_ctrl:1
	v_mov_b32_e32 v19, v18
	s_nop 1
	v_permlane16_swap_b32_e32 v18, v19
	v_add_f32_e32 v18, v18, v19
	v_mov_b32_e32 v19, v18
	s_nop 1
	v_permlane32_swap_b32_e32 v18, v19
	v_add_f32_e32 v18, v18, v19
	v_cndmask_b32_e32 v19, v51, v73, vcc
	v_mad_i64_i32 v[22:23], s[16:17], v19, s55, v[68:69]
	v_lshl_add_u64 v[20:21], v[22:23], 0, s[34:35]
	v_lshl_add_u64 v[24:25], v[20:21], 0, v[0:1]
	global_load_dwordx4 v[24:27], v[24:25], off
	v_lshl_add_u64 v[22:23], v[22:23], 0, v[0:1]
	global_load_dwordx4 v[28:31], v[22:23], off
	v_fmamk_f32 v18, v18, 0x3a800000, v211
	v_rsq_f32_e32 v18, v18
	v_cmp_lt_i32_e32 vcc, s59, v50
	s_or_b64 s[8:9], vcc, s[8:9]
	v_pk_mul_f32 v[46:47], v[46:47], v[18:19] op_sel_hi:[1,0]
	v_pk_mul_f32 v[48:49], v[48:49], v[18:19] op_sel_hi:[1,0]
	v_pk_mul_f32 v[46:47], v[2:3], v[46:47]
	v_pk_mul_f32 v[48:49], v[4:5], v[48:49]
	v_pk_mul_f32 v[42:43], v[42:43], v[18:19] op_sel_hi:[1,0]
	v_pk_mul_f32 v[44:45], v[44:45], v[18:19] op_sel_hi:[1,0]
	v_pk_mul_f32 v[42:43], v[6:7], v[42:43]
	v_pk_mul_f32 v[44:45], v[8:9], v[44:45]
	v_pk_mul_f32 v[38:39], v[38:39], v[18:19] op_sel_hi:[1,0]
	v_pk_mul_f32 v[40:41], v[40:41], v[18:19] op_sel_hi:[1,0]
	v_pk_mul_f32 v[38:39], v[10:11], v[38:39]
	v_pk_mul_f32 v[40:41], v[12:13], v[40:41]
	s_waitcnt vmcnt(1)
	v_pk_add_f32 v[24:25], v[24:25], 1.0 op_sel_hi:[1,0]
	v_pk_add_f32 v[26:27], v[26:27], 1.0 op_sel_hi:[1,0]
	s_waitcnt vmcnt(0)
	v_pk_fma_f32 v[24:25], v[24:25], v[46:47], v[28:29]
	v_pk_fma_f32 v[26:27], v[26:27], v[48:49], v[30:31]
	v_cvt_pk_bf16_f32 v28, v24, v25
	v_lshl_add_u64 v[24:25], v[58:59], 0, v[32:33]
	v_cvt_pk_bf16_f32 v29, v26, v27
	global_store_dwordx2 v[24:25], v[28:29], off
	v_lshl_add_u64 v[26:27], v[20:21], 0, v[60:61]
	global_load_dwordx4 v[26:29], v[26:27], off
	s_nop 0
	global_load_dwordx4 v[30:33], v[22:23], off offset:1024
	s_waitcnt vmcnt(1)
	v_pk_add_f32 v[26:27], v[26:27], 1.0 op_sel_hi:[1,0]
	v_pk_add_f32 v[28:29], v[28:29], 1.0 op_sel_hi:[1,0]
	s_waitcnt vmcnt(0)
	v_pk_fma_f32 v[26:27], v[26:27], v[42:43], v[30:31]
	v_pk_fma_f32 v[28:29], v[28:29], v[44:45], v[32:33]
	v_cvt_pk_bf16_f32 v26, v26, v27
	s_nop 0
	v_cvt_pk_bf16_f32 v27, v28, v29
	global_store_dwordx2 v[24:25], v[26:27], off offset:512
	v_lshl_add_u64 v[26:27], v[20:21], 0, v[62:63]
	global_load_dwordx4 v[26:29], v[26:27], off
	s_nop 0
	global_load_dwordx4 v[30:33], v[22:23], off offset:2048
	v_lshl_add_u64 v[20:21], v[20:21], 0, v[64:65]
	s_waitcnt vmcnt(1)
	v_pk_add_f32 v[26:27], v[26:27], 1.0 op_sel_hi:[1,0]
	v_pk_add_f32 v[28:29], v[28:29], 1.0 op_sel_hi:[1,0]
	s_waitcnt vmcnt(0)
	v_pk_fma_f32 v[26:27], v[38:39], v[26:27], v[30:31]
	v_pk_fma_f32 v[28:29], v[40:41], v[28:29], v[32:33]
	v_cvt_pk_bf16_f32 v26, v26, v27
	v_pk_mul_f32 v[30:31], v[36:37], v[18:19] op_sel_hi:[1,0]
	v_cvt_pk_bf16_f32 v27, v28, v29
	global_store_dwordx2 v[24:25], v[26:27], off offset:1024
	global_load_dwordx4 v[26:29], v[20:21], off
	s_nop 0
	global_load_dwordx4 v[20:23], v[22:23], off offset:3072
	v_pk_mul_f32 v[18:19], v[34:35], v[18:19] op_sel_hi:[1,0]
	v_pk_mul_f32 v[30:31], v[16:17], v[30:31]
	v_pk_mul_f32 v[18:19], v[14:15], v[18:19]
	s_waitcnt vmcnt(1)
	v_pk_add_f32 v[26:27], v[26:27], 1.0 op_sel_hi:[1,0]
	v_pk_add_f32 v[28:29], v[28:29], 1.0 op_sel_hi:[1,0]
	s_waitcnt vmcnt(0)
	v_pk_fma_f32 v[18:19], v[18:19], v[26:27], v[20:21]
	v_pk_fma_f32 v[22:23], v[30:31], v[28:29], v[22:23]
	v_cvt_pk_bf16_f32 v18, v18, v19
	s_nop 0
	v_cvt_pk_bf16_f32 v19, v22, v23
	global_store_dwordx2 v[24:25], v[18:19], off offset:1536
	s_andn2_b64 exec, exec, s[8:9]
	s_cbranch_execz .LBB0_187
